# RWKV mix phase: loop-invariant mix weights hoisted out of the loop, 4 items per iteration with all loads issued up front
# speedup vs baseline: 1.0602x; 1.0067x over previous
; __device__ __forceinline__ size_t xrow(int row) { return (size_t)(row >> 11) * 2049 + 1 + (row & 2047); }
; __device__ __forceinline__ u32x4 pack8(f32x4 a, f32x4 b) { u32x4 w; w.x = pk2(a[0], a[1]); w.y = pk2(a[2], a[3]); w.z = pk2(b[0], b[1]); w.w = pk2(b[2], b[3]); return w; }
; __device__ __forceinline__ int opaque_tid() { int t = threadIdx.x; asm volatile("" : "+v"(t)); return t; }
; __device__ __forceinline__ void mix_phase(const Params& p, int j) {
;     const h16* x16 = (const h16*)(p.ws + OFF_X16);
;     h16* xr = (h16*)p.out; h16* xk = (h16*)p.out + (size_t)MTOK * 1024; h16* xv = (h16*)(p.ws + R_G16);
;     const float* mix = p.in[3] + j * 6 * 1024;
;     const size_t gtid = (size_t)blockIdx.x * 512 + opaque_tid(), nth = (size_t)gridDim.x * 512;
;     for (size_t idx = gtid; idx < (size_t)MTOK * 128; idx += nth) {
;         const int row = (int)(idx >> 7), c8 = (int)(idx & 127) * 8;
;         const h16* xp = x16 + xrow(row) * 1024 + c8;
;         float xc[8], xq[8];
;         unpack8(*(const u32x4*)xp, xc); unpack8(*(const u32x4*)(xp - 1024), xq);
; #pragma unroll
;         for (int e = 0; e < 8; ++e) xq[e] -= xc[e];
;         const size_t o = (size_t)row * 1024 + c8;
; #pragma unroll
;         for (int bsel = 0; bsel < 3; ++bsel) {
;             const f32x4 m0 = *(const f32x4*)(mix + bsel * 1024 + c8), m1 = *(const f32x4*)(mix + bsel * 1024 + c8 + 4);
;             f32x4 a, b;
; #pragma unroll
;             for (int e = 0; e < 4; ++e) { a[e] = xc[e] + xq[e] * m0[e]; b[e] = xc[4 + e] + xq[4 + e] * m1[e]; }
;             h16* dst = bsel == 0 ? xr : (bsel == 1 ? xk : xv);
;             *(u32x4*)(dst + o) = pack8(a, b);
;         }
;     }
.LBB0_68:
	v_readlane_b32 s0, v253, 13
	v_readlane_b32 s1, v253, 14
	s_andn2_b64 vcc, exec, s[0:1]
	s_mov_b64 s[18:19], -1
	v_writelane_b32 v254, s44, 21
	s_cbranch_vccnz .LBB0_687
	v_readlane_b32 s0, v253, 12
	s_cmp_lt_i32 s0, 7
	s_cbranch_scc1 .LBB0_78
	s_cmp_gt_i32 s0, 11
	s_cbranch_scc0 .LBB0_79
	s_cmp_gt_i32 s0, 13
	s_cbranch_scc0 .LBB0_80
	s_cmp_gt_i32 s0, 14
	s_cbranch_scc0 .LBB0_77
	v_mov_b32_e32 v2, v226
	v_readlane_b32 s0, v250, 40
	v_readlane_b32 s1, v250, 41
	v_ashrrev_i32_e32 v3, 31, v2
	s_nop 0
	v_lshl_add_u64 v[0:1], s[0:1], 0, v[2:3]
	s_mov_b64 s[0:1], 0x800000
	v_cmp_gt_u64_e32 vcc, s[0:1], v[0:1]
	s_and_saveexec_b64 s[0:1], vcc
	v_readlane_b32 s6, v252, 58
	v_readlane_b32 s10, v250, 42
	v_readlane_b32 s12, v252, 53
	v_readlane_b32 s7, v252, 59
	s_mov_b64 s[8:9], 0x1000
	v_readlane_b32 s11, v250, 43
	v_readlane_b32 s13, v252, 54
	s_cbranch_execz .LBB0_76
	v_readlane_b32 s2, v251, 25
	v_readlane_b32 s3, v251, 26
	s_nop 1
	v_lshl_add_u64 v[2:3], v[2:3], 3, s[2:3]
	s_mov_b64 s[2:3], 0
	v_and_b32_e32 v36, 0x3f8, v2
	v_lshlrev_b32_e32 v37, 2, v36
	v_add_u32_e32 v38, 0x1000, v37
	v_add_u32_e32 v39, 0x2000, v37
	global_load_dwordx4 v[40:43], v37, s[72:73]
	global_load_dwordx4 v[44:47], v37, s[72:73] offset:16
	global_load_dwordx4 v[48:51], v38, s[72:73]
	global_load_dwordx4 v[52:55], v38, s[72:73] offset:16
	global_load_dwordx4 v[56:59], v39, s[72:73]
	global_load_dwordx4 v[60:63], v39, s[72:73] offset:16
	v_lshlrev_b32_e32 v36, 1, v36
	v_mov_b32_e32 v37, v197
.Lmx_head:
	v_lshl_add_u64 v[64:65], s[10:11], 0, v[0:1]
	v_lshl_add_u64 v[66:67], s[10:11], 1, v[0:1]
	v_lshl_add_u64 v[68:69], s[10:11], 0, v[66:67]
	v_cmp_lt_u64_e32 vcc, s[36:37], v[68:69]
	s_cbranch_vccnz .LBB0_75
	v_alignbit_b32 v71, v1, v0, 7
	v_and_b32_e32 v71, 0x7ff, v71
	v_alignbit_b32 v70, v1, v0, 18
	v_add_u32_e32 v196, 1, v71
	v_mad_u64_u32 v[70:71], s[4:5], v70, s47, v[196:197]
	v_lshlrev_b64 v[70:71], 11, v[70:71]
	v_lshl_add_u64 v[70:71], s[12:13], 0, v[70:71]
	v_lshl_add_u64 v[70:71], v[70:71], 0, v[36:37]
	global_load_dwordx4 v[80:83], v[70:71], off
	global_load_dwordx4 v[84:87], v[70:71], off offset:-2048
	v_lshrrev_b64 v[112:113], 7, v[0:1]
	v_lshlrev_b64 v[112:113], 11, v[112:113]
	v_lshl_add_u64 v[112:113], v[112:113], 0, v[36:37]
	v_alignbit_b32 v73, v65, v64, 7
	v_and_b32_e32 v73, 0x7ff, v73
	v_alignbit_b32 v72, v65, v64, 18
	v_add_u32_e32 v196, 1, v73
	v_mad_u64_u32 v[72:73], s[4:5], v72, s47, v[196:197]
	v_lshlrev_b64 v[72:73], 11, v[72:73]
	v_lshl_add_u64 v[72:73], s[12:13], 0, v[72:73]
	v_lshl_add_u64 v[72:73], v[72:73], 0, v[36:37]
	global_load_dwordx4 v[88:91], v[72:73], off
	global_load_dwordx4 v[92:95], v[72:73], off offset:-2048
	v_lshrrev_b64 v[114:115], 7, v[64:65]
	v_lshlrev_b64 v[114:115], 11, v[114:115]
	v_lshl_add_u64 v[114:115], v[114:115], 0, v[36:37]
	v_alignbit_b32 v75, v67, v66, 7
	v_and_b32_e32 v75, 0x7ff, v75
	v_alignbit_b32 v74, v67, v66, 18
	v_add_u32_e32 v196, 1, v75
	v_mad_u64_u32 v[74:75], s[4:5], v74, s47, v[196:197]
	v_lshlrev_b64 v[74:75], 11, v[74:75]
	v_lshl_add_u64 v[74:75], s[12:13], 0, v[74:75]
	v_lshl_add_u64 v[74:75], v[74:75], 0, v[36:37]
	global_load_dwordx4 v[96:99], v[74:75], off
	global_load_dwordx4 v[100:103], v[74:75], off offset:-2048
	v_lshrrev_b64 v[116:117], 7, v[66:67]
	v_lshlrev_b64 v[116:117], 11, v[116:117]
	v_lshl_add_u64 v[116:117], v[116:117], 0, v[36:37]
	v_alignbit_b32 v77, v69, v68, 7
	v_and_b32_e32 v77, 0x7ff, v77
	v_alignbit_b32 v76, v69, v68, 18
	v_add_u32_e32 v196, 1, v77
	v_mad_u64_u32 v[76:77], s[4:5], v76, s47, v[196:197]
	v_lshlrev_b64 v[76:77], 11, v[76:77]
	v_lshl_add_u64 v[76:77], s[12:13], 0, v[76:77]
	v_lshl_add_u64 v[76:77], v[76:77], 0, v[36:37]
	global_load_dwordx4 v[104:107], v[76:77], off
	global_load_dwordx4 v[108:111], v[76:77], off offset:-2048
	v_lshrrev_b64 v[118:119], 7, v[68:69]
	v_lshlrev_b64 v[118:119], 11, v[118:119]
	v_lshl_add_u64 v[118:119], v[118:119], 0, v[36:37]
	s_waitcnt vmcnt(6)
	v_cvt_f32_f16_e32 v4, v80
	v_cvt_f32_f16_sdwa v5, v80 dst_sel:DWORD dst_unused:UNUSED_PAD src0_sel:WORD_1
	v_cvt_f32_f16_e32 v12, v84
	v_cvt_f32_f16_sdwa v13, v84 dst_sel:DWORD dst_unused:UNUSED_PAD src0_sel:WORD_1
	v_cvt_f32_f16_e32 v6, v81
	v_cvt_f32_f16_sdwa v7, v81 dst_sel:DWORD dst_unused:UNUSED_PAD src0_sel:WORD_1
	v_cvt_f32_f16_e32 v14, v85
	v_cvt_f32_f16_sdwa v15, v85 dst_sel:DWORD dst_unused:UNUSED_PAD src0_sel:WORD_1
	v_cvt_f32_f16_e32 v8, v82
	v_cvt_f32_f16_sdwa v9, v82 dst_sel:DWORD dst_unused:UNUSED_PAD src0_sel:WORD_1
	v_cvt_f32_f16_e32 v16, v86
	v_cvt_f32_f16_sdwa v17, v86 dst_sel:DWORD dst_unused:UNUSED_PAD src0_sel:WORD_1
	v_cvt_f32_f16_e32 v10, v83
	v_cvt_f32_f16_sdwa v11, v83 dst_sel:DWORD dst_unused:UNUSED_PAD src0_sel:WORD_1
	v_cvt_f32_f16_e32 v18, v87
	v_cvt_f32_f16_sdwa v19, v87 dst_sel:DWORD dst_unused:UNUSED_PAD src0_sel:WORD_1
	v_pk_add_f32 v[12:13], v[12:13], v[4:5] neg_lo:[0,1] neg_hi:[0,1]
	v_pk_add_f32 v[14:15], v[14:15], v[6:7] neg_lo:[0,1] neg_hi:[0,1]
	v_pk_add_f32 v[16:17], v[16:17], v[8:9] neg_lo:[0,1] neg_hi:[0,1]
	v_pk_add_f32 v[18:19], v[18:19], v[10:11] neg_lo:[0,1] neg_hi:[0,1]
	v_pk_fma_f32 v[20:21], v[40:41], v[12:13], v[4:5]
	v_pk_fma_f32 v[22:23], v[42:43], v[14:15], v[6:7]
	v_pk_fma_f32 v[24:25], v[44:45], v[16:17], v[8:9]
	v_pk_fma_f32 v[26:27], v[46:47], v[18:19], v[10:11]
	v_cvt_pk_f16_f32 v28, v20, v21
	v_cvt_pk_f16_f32 v29, v22, v23
	v_cvt_pk_f16_f32 v30, v24, v25
	v_cvt_pk_f16_f32 v31, v26, v27
	v_lshl_add_u64 v[32:33], s[38:39], 0, v[112:113]
	global_store_dwordx4 v[32:33], v[28:31], off
	v_pk_fma_f32 v[20:21], v[48:49], v[12:13], v[4:5]
	v_pk_fma_f32 v[22:23], v[50:51], v[14:15], v[6:7]
	v_pk_fma_f32 v[24:25], v[52:53], v[16:17], v[8:9]
	v_pk_fma_f32 v[26:27], v[54:55], v[18:19], v[10:11]
	v_cvt_pk_f16_f32 v28, v20, v21
	v_cvt_pk_f16_f32 v29, v22, v23
	v_cvt_pk_f16_f32 v30, v24, v25
	v_cvt_pk_f16_f32 v31, v26, v27
	v_lshl_add_u64 v[32:33], s[40:41], 0, v[112:113]
	global_store_dwordx4 v[32:33], v[28:31], off
	v_pk_fma_f32 v[20:21], v[56:57], v[12:13], v[4:5]
	v_pk_fma_f32 v[22:23], v[58:59], v[14:15], v[6:7]
	v_pk_fma_f32 v[24:25], v[60:61], v[16:17], v[8:9]
	v_pk_fma_f32 v[26:27], v[62:63], v[18:19], v[10:11]
	v_cvt_pk_f16_f32 v28, v20, v21
	v_cvt_pk_f16_f32 v29, v22, v23
	v_cvt_pk_f16_f32 v30, v24, v25
	v_cvt_pk_f16_f32 v31, v26, v27
	v_lshl_add_u64 v[32:33], s[54:55], 0, v[112:113]
	global_store_dwordx4 v[32:33], v[28:31], off
	s_waitcnt vmcnt(7)
; __device__ __forceinline__ size_t xrow(int row) { return (size_t)(row >> 11) * 2049 + 1 + (row & 2047); }
; __device__ __forceinline__ u32x4 pack8(f32x4 a, f32x4 b) { u32x4 w; w.x = pk2(a[0], a[1]); w.y = pk2(a[2], a[3]); w.z = pk2(b[0], b[1]); w.w = pk2(b[2], b[3]); return w; }
; __device__ __forceinline__ void mix_phase(const Params& p, int j) {
;     ...
;     for (size_t idx = gtid; idx < (size_t)MTOK * 128; idx += nth) {
;         const int row = (int)(idx >> 7), c8 = (int)(idx & 127) * 8;
;         const h16* xp = x16 + xrow(row) * 1024 + c8;
;         float xc[8], xq[8];
;         unpack8(*(const u32x4*)xp, xc); unpack8(*(const u32x4*)(xp - 1024), xq);
; #pragma unroll
;         for (int e = 0; e < 8; ++e) xq[e] -= xc[e];
;         const size_t o = (size_t)row * 1024 + c8;
; #pragma unroll
;         for (int bsel = 0; bsel < 3; ++bsel) {
;             const f32x4 m0 = *(const f32x4*)(mix + bsel * 1024 + c8), m1 = *(const f32x4*)(mix + bsel * 1024 + c8 + 4);
;             f32x4 a, b;
; #pragma unroll
;             for (int e = 0; e < 4; ++e) { a[e] = xc[e] + xq[e] * m0[e]; b[e] = xc[4 + e] + xq[4 + e] * m1[e]; }
;             h16* dst = bsel == 0 ? xr : (bsel == 1 ? xk : xv);
;             *(u32x4*)(dst + o) = pack8(a, b);
;         }
	v_cvt_f32_f16_e32 v4, v88
	v_cvt_f32_f16_sdwa v5, v88 dst_sel:DWORD dst_unused:UNUSED_PAD src0_sel:WORD_1
	v_cvt_f32_f16_e32 v12, v92
	v_cvt_f32_f16_sdwa v13, v92 dst_sel:DWORD dst_unused:UNUSED_PAD src0_sel:WORD_1
	v_cvt_f32_f16_e32 v6, v89
	v_cvt_f32_f16_sdwa v7, v89 dst_sel:DWORD dst_unused:UNUSED_PAD src0_sel:WORD_1
	v_cvt_f32_f16_e32 v14, v93
	v_cvt_f32_f16_sdwa v15, v93 dst_sel:DWORD dst_unused:UNUSED_PAD src0_sel:WORD_1
	v_cvt_f32_f16_e32 v8, v90
	v_cvt_f32_f16_sdwa v9, v90 dst_sel:DWORD dst_unused:UNUSED_PAD src0_sel:WORD_1
	v_cvt_f32_f16_e32 v16, v94
	v_cvt_f32_f16_sdwa v17, v94 dst_sel:DWORD dst_unused:UNUSED_PAD src0_sel:WORD_1
	v_cvt_f32_f16_e32 v10, v91
	v_cvt_f32_f16_sdwa v11, v91 dst_sel:DWORD dst_unused:UNUSED_PAD src0_sel:WORD_1
	v_cvt_f32_f16_e32 v18, v95
	v_cvt_f32_f16_sdwa v19, v95 dst_sel:DWORD dst_unused:UNUSED_PAD src0_sel:WORD_1
	v_pk_add_f32 v[12:13], v[12:13], v[4:5] neg_lo:[0,1] neg_hi:[0,1]
	v_pk_add_f32 v[14:15], v[14:15], v[6:7] neg_lo:[0,1] neg_hi:[0,1]
	v_pk_add_f32 v[16:17], v[16:17], v[8:9] neg_lo:[0,1] neg_hi:[0,1]
	v_pk_add_f32 v[18:19], v[18:19], v[10:11] neg_lo:[0,1] neg_hi:[0,1]
	v_pk_fma_f32 v[20:21], v[40:41], v[12:13], v[4:5]
	v_pk_fma_f32 v[22:23], v[42:43], v[14:15], v[6:7]
	v_pk_fma_f32 v[24:25], v[44:45], v[16:17], v[8:9]
	v_pk_fma_f32 v[26:27], v[46:47], v[18:19], v[10:11]
	v_cvt_pk_f16_f32 v28, v20, v21
	v_cvt_pk_f16_f32 v29, v22, v23
	v_cvt_pk_f16_f32 v30, v24, v25
	v_cvt_pk_f16_f32 v31, v26, v27
	v_lshl_add_u64 v[32:33], s[38:39], 0, v[114:115]
	global_store_dwordx4 v[32:33], v[28:31], off
	v_pk_fma_f32 v[20:21], v[48:49], v[12:13], v[4:5]
	v_pk_fma_f32 v[22:23], v[50:51], v[14:15], v[6:7]
	v_pk_fma_f32 v[24:25], v[52:53], v[16:17], v[8:9]
	v_pk_fma_f32 v[26:27], v[54:55], v[18:19], v[10:11]
	v_cvt_pk_f16_f32 v28, v20, v21
	v_cvt_pk_f16_f32 v29, v22, v23
	v_cvt_pk_f16_f32 v30, v24, v25
	v_cvt_pk_f16_f32 v31, v26, v27
	v_lshl_add_u64 v[32:33], s[40:41], 0, v[114:115]
	global_store_dwordx4 v[32:33], v[28:31], off
	v_pk_fma_f32 v[20:21], v[56:57], v[12:13], v[4:5]
	v_pk_fma_f32 v[22:23], v[58:59], v[14:15], v[6:7]
	v_pk_fma_f32 v[24:25], v[60:61], v[16:17], v[8:9]
	v_pk_fma_f32 v[26:27], v[62:63], v[18:19], v[10:11]
	v_cvt_pk_f16_f32 v28, v20, v21
	v_cvt_pk_f16_f32 v29, v22, v23
	v_cvt_pk_f16_f32 v30, v24, v25
	v_cvt_pk_f16_f32 v31, v26, v27
	v_lshl_add_u64 v[32:33], s[54:55], 0, v[114:115]
	global_store_dwordx4 v[32:33], v[28:31], off
	s_waitcnt vmcnt(8)
	v_cvt_f32_f16_e32 v4, v96
	v_cvt_f32_f16_sdwa v5, v96 dst_sel:DWORD dst_unused:UNUSED_PAD src0_sel:WORD_1
	v_cvt_f32_f16_e32 v12, v100
	v_cvt_f32_f16_sdwa v13, v100 dst_sel:DWORD dst_unused:UNUSED_PAD src0_sel:WORD_1
	v_cvt_f32_f16_e32 v6, v97
	v_cvt_f32_f16_sdwa v7, v97 dst_sel:DWORD dst_unused:UNUSED_PAD src0_sel:WORD_1
	v_cvt_f32_f16_e32 v14, v101
	v_cvt_f32_f16_sdwa v15, v101 dst_sel:DWORD dst_unused:UNUSED_PAD src0_sel:WORD_1
	v_cvt_f32_f16_e32 v8, v98
	v_cvt_f32_f16_sdwa v9, v98 dst_sel:DWORD dst_unused:UNUSED_PAD src0_sel:WORD_1
	v_cvt_f32_f16_e32 v16, v102
	v_cvt_f32_f16_sdwa v17, v102 dst_sel:DWORD dst_unused:UNUSED_PAD src0_sel:WORD_1
	v_cvt_f32_f16_e32 v10, v99
	v_cvt_f32_f16_sdwa v11, v99 dst_sel:DWORD dst_unused:UNUSED_PAD src0_sel:WORD_1
	v_cvt_f32_f16_e32 v18, v103
	v_cvt_f32_f16_sdwa v19, v103 dst_sel:DWORD dst_unused:UNUSED_PAD src0_sel:WORD_1
	v_pk_add_f32 v[12:13], v[12:13], v[4:5] neg_lo:[0,1] neg_hi:[0,1]
	v_pk_add_f32 v[14:15], v[14:15], v[6:7] neg_lo:[0,1] neg_hi:[0,1]
	v_pk_add_f32 v[16:17], v[16:17], v[8:9] neg_lo:[0,1] neg_hi:[0,1]
	v_pk_add_f32 v[18:19], v[18:19], v[10:11] neg_lo:[0,1] neg_hi:[0,1]
	v_pk_fma_f32 v[20:21], v[40:41], v[12:13], v[4:5]
	v_pk_fma_f32 v[22:23], v[42:43], v[14:15], v[6:7]
	v_pk_fma_f32 v[24:25], v[44:45], v[16:17], v[8:9]
	v_pk_fma_f32 v[26:27], v[46:47], v[18:19], v[10:11]
	v_cvt_pk_f16_f32 v28, v20, v21
	v_cvt_pk_f16_f32 v29, v22, v23
	v_cvt_pk_f16_f32 v30, v24, v25
	v_cvt_pk_f16_f32 v31, v26, v27
	v_lshl_add_u64 v[32:33], s[38:39], 0, v[116:117]
	global_store_dwordx4 v[32:33], v[28:31], off
	v_pk_fma_f32 v[20:21], v[48:49], v[12:13], v[4:5]
	v_pk_fma_f32 v[22:23], v[50:51], v[14:15], v[6:7]
	v_pk_fma_f32 v[24:25], v[52:53], v[16:17], v[8:9]
	v_pk_fma_f32 v[26:27], v[54:55], v[18:19], v[10:11]
	v_cvt_pk_f16_f32 v28, v20, v21
	v_cvt_pk_f16_f32 v29, v22, v23
	v_cvt_pk_f16_f32 v30, v24, v25
	v_cvt_pk_f16_f32 v31, v26, v27
	v_lshl_add_u64 v[32:33], s[40:41], 0, v[116:117]
	global_store_dwordx4 v[32:33], v[28:31], off
	v_pk_fma_f32 v[20:21], v[56:57], v[12:13], v[4:5]
	v_pk_fma_f32 v[22:23], v[58:59], v[14:15], v[6:7]
	v_pk_fma_f32 v[24:25], v[60:61], v[16:17], v[8:9]
	v_pk_fma_f32 v[26:27], v[62:63], v[18:19], v[10:11]
	v_cvt_pk_f16_f32 v28, v20, v21
	v_cvt_pk_f16_f32 v29, v22, v23
	v_cvt_pk_f16_f32 v30, v24, v25
	v_cvt_pk_f16_f32 v31, v26, v27
	v_lshl_add_u64 v[32:33], s[54:55], 0, v[116:117]
	global_store_dwordx4 v[32:33], v[28:31], off
	s_waitcnt vmcnt(9)
; __device__ __forceinline__ size_t xrow(int row) { return (size_t)(row >> 11) * 2049 + 1 + (row & 2047); }
; __device__ __forceinline__ u32x4 pack8(f32x4 a, f32x4 b) { u32x4 w; w.x = pk2(a[0], a[1]); w.y = pk2(a[2], a[3]); w.z = pk2(b[0], b[1]); w.w = pk2(b[2], b[3]); return w; }
; __device__ __forceinline__ void mix_phase(const Params& p, int j) {
;     ...
;     for (size_t idx = gtid; idx < (size_t)MTOK * 128; idx += nth) {
;         const int row = (int)(idx >> 7), c8 = (int)(idx & 127) * 8;
;         const h16* xp = x16 + xrow(row) * 1024 + c8;
;         float xc[8], xq[8];
;         unpack8(*(const u32x4*)xp, xc); unpack8(*(const u32x4*)(xp - 1024), xq);
; #pragma unroll
;         for (int e = 0; e < 8; ++e) xq[e] -= xc[e];
;         const size_t o = (size_t)row * 1024 + c8;
; #pragma unroll
;         for (int bsel = 0; bsel < 3; ++bsel) {
;             const f32x4 m0 = *(const f32x4*)(mix + bsel * 1024 + c8), m1 = *(const f32x4*)(mix + bsel * 1024 + c8 + 4);
;             f32x4 a, b;
; #pragma unroll
;             for (int e = 0; e < 4; ++e) { a[e] = xc[e] + xq[e] * m0[e]; b[e] = xc[4 + e] + xq[4 + e] * m1[e]; }
;             h16* dst = bsel == 0 ? xr : (bsel == 1 ? xk : xv);
;             *(u32x4*)(dst + o) = pack8(a, b);
;         }
	v_cvt_f32_f16_e32 v4, v104
	v_cvt_f32_f16_sdwa v5, v104 dst_sel:DWORD dst_unused:UNUSED_PAD src0_sel:WORD_1
	v_cvt_f32_f16_e32 v12, v108
	v_cvt_f32_f16_sdwa v13, v108 dst_sel:DWORD dst_unused:UNUSED_PAD src0_sel:WORD_1
	v_cvt_f32_f16_e32 v6, v105
	v_cvt_f32_f16_sdwa v7, v105 dst_sel:DWORD dst_unused:UNUSED_PAD src0_sel:WORD_1
	v_cvt_f32_f16_e32 v14, v109
	v_cvt_f32_f16_sdwa v15, v109 dst_sel:DWORD dst_unused:UNUSED_PAD src0_sel:WORD_1
	v_cvt_f32_f16_e32 v8, v106
	v_cvt_f32_f16_sdwa v9, v106 dst_sel:DWORD dst_unused:UNUSED_PAD src0_sel:WORD_1
	v_cvt_f32_f16_e32 v16, v110
	v_cvt_f32_f16_sdwa v17, v110 dst_sel:DWORD dst_unused:UNUSED_PAD src0_sel:WORD_1
	v_cvt_f32_f16_e32 v10, v107
	v_cvt_f32_f16_sdwa v11, v107 dst_sel:DWORD dst_unused:UNUSED_PAD src0_sel:WORD_1
	v_cvt_f32_f16_e32 v18, v111
	v_cvt_f32_f16_sdwa v19, v111 dst_sel:DWORD dst_unused:UNUSED_PAD src0_sel:WORD_1
	v_pk_add_f32 v[12:13], v[12:13], v[4:5] neg_lo:[0,1] neg_hi:[0,1]
	v_pk_add_f32 v[14:15], v[14:15], v[6:7] neg_lo:[0,1] neg_hi:[0,1]
	v_pk_add_f32 v[16:17], v[16:17], v[8:9] neg_lo:[0,1] neg_hi:[0,1]
	v_pk_add_f32 v[18:19], v[18:19], v[10:11] neg_lo:[0,1] neg_hi:[0,1]
	v_pk_fma_f32 v[20:21], v[40:41], v[12:13], v[4:5]
	v_pk_fma_f32 v[22:23], v[42:43], v[14:15], v[6:7]
	v_pk_fma_f32 v[24:25], v[44:45], v[16:17], v[8:9]
	v_pk_fma_f32 v[26:27], v[46:47], v[18:19], v[10:11]
	v_cvt_pk_f16_f32 v28, v20, v21
	v_cvt_pk_f16_f32 v29, v22, v23
	v_cvt_pk_f16_f32 v30, v24, v25
	v_cvt_pk_f16_f32 v31, v26, v27
	v_lshl_add_u64 v[32:33], s[38:39], 0, v[118:119]
	global_store_dwordx4 v[32:33], v[28:31], off
	v_pk_fma_f32 v[20:21], v[48:49], v[12:13], v[4:5]
	v_pk_fma_f32 v[22:23], v[50:51], v[14:15], v[6:7]
	v_pk_fma_f32 v[24:25], v[52:53], v[16:17], v[8:9]
	v_pk_fma_f32 v[26:27], v[54:55], v[18:19], v[10:11]
	v_cvt_pk_f16_f32 v28, v20, v21
	v_cvt_pk_f16_f32 v29, v22, v23
	v_cvt_pk_f16_f32 v30, v24, v25
	v_cvt_pk_f16_f32 v31, v26, v27
	v_lshl_add_u64 v[32:33], s[40:41], 0, v[118:119]
	global_store_dwordx4 v[32:33], v[28:31], off
	v_pk_fma_f32 v[20:21], v[56:57], v[12:13], v[4:5]
	v_pk_fma_f32 v[22:23], v[58:59], v[14:15], v[6:7]
	v_pk_fma_f32 v[24:25], v[60:61], v[16:17], v[8:9]
	v_pk_fma_f32 v[26:27], v[62:63], v[18:19], v[10:11]
	v_cvt_pk_f16_f32 v28, v20, v21
	v_cvt_pk_f16_f32 v29, v22, v23
	v_cvt_pk_f16_f32 v30, v24, v25
	v_cvt_pk_f16_f32 v31, v26, v27
	v_lshl_add_u64 v[32:33], s[54:55], 0, v[118:119]
	global_store_dwordx4 v[32:33], v[28:31], off
	v_lshl_add_u64 v[0:1], s[10:11], 2, v[0:1]
	v_lshl_add_u64 v[2:3], s[6:7], 2, v[2:3]
	v_cmp_lt_u64_e32 vcc, s[36:37], v[0:1]
	s_or_b64 s[2:3], vcc, s[2:3]
	s_andn2_b64 exec, exec, s[2:3]
	s_cbranch_execnz .Lmx_head
	s_branch .LBB0_76
